# same as previous sgu staging load batching, with the 2-state pad between v_add_co and v_addc of the prefetch address adds
# speedup vs baseline: 1.0113x; 1.0033x over previous
.LBB0_287:
	global_load_ushort v6, v[4:5], off offset:128
	global_load_ushort v7, v[4:5], off
	global_load_ushort v14, v[4:5], off offset:-256
	global_load_ushort v15, v[4:5], off offset:-128
	global_load_dword v20, v[0:1], off offset:256
	global_load_dword v21, v[0:1], off offset:512
	global_load_dword v22, v[0:1], off offset:768
	v_add_co_u32_e32 v192, vcc, 0x9000, v4
	s_nop 1
	v_addc_co_u32_e32 v193, vcc, 0, v5, vcc
	global_load_ushort v200, v[192:193], off offset:-256
	global_load_ushort v201, v[192:193], off offset:-128
	global_load_ushort v202, v[192:193], off
	global_load_ushort v203, v[192:193], off offset:128
	v_add_co_u32_e32 v194, vcc, 0x9000, v192
	s_nop 1
	v_addc_co_u32_e32 v195, vcc, 0, v193, vcc
	global_load_ushort v204, v[194:195], off offset:-256
	global_load_ushort v205, v[194:195], off offset:-128
	global_load_ushort v206, v[194:195], off
	global_load_ushort v207, v[194:195], off offset:128
	v_add_co_u32_e32 v196, vcc, 0x9000, v194
	s_nop 1
	v_addc_co_u32_e32 v197, vcc, 0, v195, vcc
	global_load_ushort v208, v[196:197], off offset:-256
	global_load_ushort v209, v[196:197], off offset:-128
	global_load_ushort v210, v[196:197], off
	global_load_ushort v211, v[196:197], off offset:128
	s_add_i32 s3, s22, s24
	s_mul_i32 s2, s3, 0x1200
	s_add_i32 s8, s3, 8
	s_mul_hi_u32 s9, s8, 0x1200
	s_add_i32 s8, s2, 0x9000
	s_add_u32 s8, s4, s8
	s_addc_u32 s9, s5, s9
	s_waitcnt vmcnt(18)
	v_lshlrev_b32_e32 v6, 16, v6
	s_waitcnt vmcnt(17)
	v_lshlrev_b32_e32 v7, 16, v7
	v_mul_f32_e32 v10, 0x3d372713, v7
	v_mul_f32_e32 v10, v10, v7
	v_mov_b32_e32 v11, v7
	v_fmac_f32_e32 v11, v10, v11
	v_mul_f32_e32 v10, 0x3f4c422a, v11
	v_add_f32_e32 v10, v10, v10
	v_mul_f32_e32 v10, 0x3fb8aa3b, v10
	s_waitcnt vmcnt(16)
	v_lshlrev_b32_e32 v14, 16, v14
	v_exp_f32_e32 v10, v10
	v_mul_f32_e32 v16, 0x3d372713, v14
	v_mul_f32_e32 v16, v16, v14
	v_mov_b32_e32 v17, v14
	s_waitcnt vmcnt(15)
	v_lshlrev_b32_e32 v15, 16, v15
	v_fmac_f32_e32 v17, v16, v17
	v_mul_f32_e32 v16, 0x3f4c422a, v17
	v_mul_f32_e32 v17, 0x3d372713, v15
	v_add_f32_e32 v10, 1.0, v10
	v_mul_f32_e32 v17, v17, v15
	v_mov_b32_e32 v18, v15
	v_rcp_f32_e32 v11, v10
	v_mul_f32_e32 v10, 0x3d372713, v6
	v_fmac_f32_e32 v18, v17, v18
	v_mul_f32_e32 v10, v10, v6
	v_mov_b32_e32 v12, v6
	v_mul_f32_e32 v17, 0x3f4c422a, v18
	v_fmac_f32_e32 v12, v10, v12
	v_add_f32_e32 v16, v16, v16
	v_add_f32_e32 v17, v17, v17
	v_mul_f32_e32 v10, 0x3f4c422a, v12
	v_mul_f32_e32 v16, 0x3fb8aa3b, v16
	v_mul_f32_e32 v17, 0x3fb8aa3b, v17
	v_add_f32_e32 v10, v10, v10
	v_exp_f32_e32 v16, v16
	v_exp_f32_e32 v17, v17
	v_mul_f32_e32 v10, 0x3fb8aa3b, v10
	v_exp_f32_e32 v10, v10
	v_add_f32_e32 v16, 1.0, v16
	v_add_f32_e32 v17, 1.0, v17
	v_rcp_f32_e32 v16, v16
	v_rcp_f32_e32 v17, v17
	v_add_f32_e32 v10, 1.0, v10
	v_rcp_f32_e32 v10, v10
	v_pk_mul_f32 v[14:15], v[14:15], 0.5 op_sel_hi:[1,0]
	v_pk_fma_f32 v[16:17], v[16:17], 2.0, 1.0 op_sel_hi:[1,0,0] neg_lo:[1,0,0] neg_hi:[1,0,0]
	v_pk_mul_f32 v[6:7], v[6:7], 0.5 op_sel_hi:[1,0]
	v_pk_add_f32 v[16:17], v[16:17], 1.0 op_sel_hi:[1,0]
	v_pk_fma_f32 v[10:11], v[10:11], 2.0, 1.0 op_sel_hi:[1,0,0] neg_lo:[1,0,0] neg_hi:[1,0,0]
	v_pk_mul_f32 v[18:19], v[14:15], v[16:17]
	v_pk_add_f32 v[10:11], v[10:11], 1.0 op_sel_hi:[1,0]
	v_add_f32_e32 v18, 0, v18
	v_pk_mul_f32 v[12:13], v[6:7], v[10:11]
	v_add_f32_e32 v18, v18, v19
	v_add_f32_e32 v13, v18, v13
	v_add_f32_e32 v12, v13, v12
	s_nop 1
	v_add_f32_dpp v12, v12, v12 quad_perm:[1,0,3,2] row_mask:0xf bank_mask:0xf
	s_nop 1
	v_add_f32_dpp v12, v12, v12 quad_perm:[2,3,0,1] row_mask:0xf bank_mask:0xf
	s_nop 1
	v_add_f32_dpp v12, v12, v12 row_half_mirror row_mask:0xf bank_mask:0xf
	s_nop 1
	v_add_f32_dpp v12, v12, v12 row_mirror row_mask:0xf bank_mask:0xf
	ds_bpermute_b32 v13, v53, v12
	s_waitcnt lgkmcnt(0)
	v_add_f32_e32 v12, v12, v13
	ds_bpermute_b32 v13, v54, v12
	s_waitcnt lgkmcnt(0)
	v_add_f32_e32 v12, v12, v13
	v_mul_f32_e32 v12, 0x3b800000, v12
	v_pk_fma_f32 v[14:15], v[14:15], v[16:17], v[12:13] op_sel_hi:[1,1,0] neg_lo:[0,0,1] neg_hi:[0,0,1]
	v_pk_fma_f32 v[6:7], v[6:7], v[10:11], v[12:13] op_sel_hi:[1,1,0] neg_lo:[0,0,1] neg_hi:[0,0,1]
	v_pk_mul_f32 v[16:17], v[14:15], v[14:15]
	v_pk_mul_f32 v[10:11], v[6:7], v[6:7]
	v_add_f32_e32 v12, v16, v17
	v_add_f32_e32 v11, v11, v12
	v_add_f32_e32 v10, v10, v11
	s_nop 1
	v_add_f32_dpp v10, v10, v10 quad_perm:[1,0,3,2] row_mask:0xf bank_mask:0xf
	s_nop 1
	v_add_f32_dpp v10, v10, v10 quad_perm:[2,3,0,1] row_mask:0xf bank_mask:0xf
	s_nop 1
	v_add_f32_dpp v10, v10, v10 row_half_mirror row_mask:0xf bank_mask:0xf
	s_nop 1
	v_add_f32_dpp v10, v10, v10 row_mirror row_mask:0xf bank_mask:0xf
	ds_bpermute_b32 v11, v53, v10
	s_waitcnt lgkmcnt(0)
	v_add_f32_e32 v10, v10, v11
	ds_bpermute_b32 v11, v54, v10
	s_waitcnt lgkmcnt(0)
	v_add_f32_e32 v10, v10, v11
	v_fmamk_f32 v10, v10, 0x3b800000, v176
	v_cmp_gt_f32_e32 vcc, s75, v10
	v_mul_f32_e32 v11, 0x4b800000, v10
	s_nop 0
	v_cndmask_b32_e32 v10, v10, v11, vcc
	v_rsq_f32_e32 v10, v10
	s_nop 0
	v_mul_f32_e32 v11, 0x45800000, v10
	v_cndmask_b32_e32 v10, v10, v11, vcc
	v_mul_f32_e32 v11, v14, v10
	v_mul_f32_e32 v11, v8, v11
	v_cvt_pk_bf16_f32 v11, v11, v2
	v_mul_f32_e32 v7, v7, v10
	v_mul_f32_e32 v6, v6, v10
	ds_write_b16 v9, v11
	v_mul_f32_e32 v11, v15, v10
	s_waitcnt vmcnt(13)
	v_mul_f32_e32 v7, v21, v7
	s_waitcnt vmcnt(12)
	v_mul_f32_e32 v6, v22, v6
	v_mul_f32_e32 v11, v20, v11
	v_cvt_pk_bf16_f32 v7, v7, v2
	v_cvt_pk_bf16_f32 v6, v6, v2
	v_cvt_pk_bf16_f32 v11, v11, v2
	ds_write_b16 v9, v7 offset:33792
	ds_write_b16 v9, v6 offset:50688
	v_lshl_add_u64 v[6:7], s[8:9], 0, v[40:41]
	ds_write_b16 v9, v11 offset:16896
	v_lshl_add_u64 v[10:11], v[6:7], 0, s[96:97]
	s_waitcnt vmcnt(8)
	v_mov_b32_e32 v12, v203
	v_mov_b32_e32 v13, v202
	v_add_co_u32_e32 v6, vcc, s74, v6
	s_add_i32 s8, s3, 16
	s_nop 0
	v_addc_co_u32_e32 v7, vcc, 0, v7, vcc
	v_mov_b32_e32 v6, v200
	s_nop 0
	v_mov_b32_e32 v7, v201
	s_mul_hi_u32 s9, s8, 0x1200
	s_add_i32 s8, s2, 0x12000
	s_add_u32 s8, s4, s8
	s_addc_u32 s9, s5, s9
	s_add_i32 s3, s3, 24
	s_add_i32 s2, s2, 0x1b000
	s_mul_hi_u32 s3, s3, 0x1200
	s_add_u32 s2, s4, s2
	s_addc_u32 s3, s5, s3
	s_add_i32 s24, s24, 32
	s_cmpk_eq_i32 s24, 0x80
	v_lshlrev_b32_e32 v12, 16, v12
	v_lshlrev_b32_e32 v13, 16, v13
	v_mul_f32_e32 v14, 0x3d372713, v13
	v_mul_f32_e32 v14, v14, v13
	v_mov_b32_e32 v15, v13
	v_fmac_f32_e32 v15, v14, v15
	v_mul_f32_e32 v14, 0x3f4c422a, v15
	v_add_f32_e32 v14, v14, v14
	v_mul_f32_e32 v14, 0x3fb8aa3b, v14
	v_lshlrev_b32_e32 v6, 16, v6
	v_exp_f32_e32 v14, v14
	v_mul_f32_e32 v10, 0x3d372713, v6
	v_mul_f32_e32 v10, v10, v6
	v_mov_b32_e32 v11, v6
	v_lshlrev_b32_e32 v7, 16, v7
	v_fmac_f32_e32 v11, v10, v11
	v_mul_f32_e32 v10, 0x3f4c422a, v11
	v_mul_f32_e32 v11, 0x3d372713, v7
	v_add_f32_e32 v14, 1.0, v14
	v_mul_f32_e32 v11, v11, v7
	v_mov_b32_e32 v18, v7
	v_rcp_f32_e32 v15, v14
	v_mul_f32_e32 v14, 0x3d372713, v12
	v_fmac_f32_e32 v18, v11, v18
	v_mul_f32_e32 v14, v14, v12
	v_mov_b32_e32 v16, v12
	v_mul_f32_e32 v11, 0x3f4c422a, v18
	v_fmac_f32_e32 v16, v14, v16
	v_add_f32_e32 v10, v10, v10
	v_add_f32_e32 v11, v11, v11
	v_mul_f32_e32 v14, 0x3f4c422a, v16
	v_mul_f32_e32 v10, 0x3fb8aa3b, v10
	v_mul_f32_e32 v11, 0x3fb8aa3b, v11
	v_add_f32_e32 v14, v14, v14
	v_exp_f32_e32 v10, v10
	v_exp_f32_e32 v11, v11
	v_mul_f32_e32 v14, 0x3fb8aa3b, v14
	v_exp_f32_e32 v14, v14
	v_add_f32_e32 v10, 1.0, v10
	v_add_f32_e32 v11, 1.0, v11
	v_rcp_f32_e32 v10, v10
	v_rcp_f32_e32 v11, v11
	v_add_f32_e32 v14, 1.0, v14
	v_rcp_f32_e32 v14, v14
	v_pk_mul_f32 v[6:7], v[6:7], 0.5 op_sel_hi:[1,0]
	v_pk_fma_f32 v[10:11], v[10:11], 2.0, 1.0 op_sel_hi:[1,0,0] neg_lo:[1,0,0] neg_hi:[1,0,0]
	v_pk_mul_f32 v[12:13], v[12:13], 0.5 op_sel_hi:[1,0]
	v_pk_add_f32 v[10:11], v[10:11], 1.0 op_sel_hi:[1,0]
	v_pk_fma_f32 v[14:15], v[14:15], 2.0, 1.0 op_sel_hi:[1,0,0] neg_lo:[1,0,0] neg_hi:[1,0,0]
	v_pk_mul_f32 v[18:19], v[6:7], v[10:11]
	v_pk_add_f32 v[14:15], v[14:15], 1.0 op_sel_hi:[1,0]
	v_add_f32_e32 v18, 0, v18
	v_pk_mul_f32 v[16:17], v[12:13], v[14:15]
	v_add_f32_e32 v18, v18, v19
	v_add_f32_e32 v17, v18, v17
	v_add_f32_e32 v16, v17, v16
	s_nop 1
	v_add_f32_dpp v16, v16, v16 quad_perm:[1,0,3,2] row_mask:0xf bank_mask:0xf
	s_nop 1
	v_add_f32_dpp v16, v16, v16 quad_perm:[2,3,0,1] row_mask:0xf bank_mask:0xf
	s_nop 1
	v_add_f32_dpp v16, v16, v16 row_half_mirror row_mask:0xf bank_mask:0xf
	s_nop 1
	v_add_f32_dpp v16, v16, v16 row_mirror row_mask:0xf bank_mask:0xf
	ds_bpermute_b32 v17, v53, v16
	s_waitcnt lgkmcnt(0)
	v_add_f32_e32 v16, v16, v17
	ds_bpermute_b32 v17, v54, v16
	s_waitcnt lgkmcnt(0)
	v_add_f32_e32 v16, v16, v17
	v_mul_f32_e32 v16, 0x3b800000, v16
	v_pk_fma_f32 v[6:7], v[6:7], v[10:11], v[16:17] op_sel_hi:[1,1,0] neg_lo:[0,0,1] neg_hi:[0,0,1]
	v_pk_fma_f32 v[12:13], v[12:13], v[14:15], v[16:17] op_sel_hi:[1,1,0] neg_lo:[0,0,1] neg_hi:[0,0,1]
	v_pk_mul_f32 v[10:11], v[6:7], v[6:7]
	v_pk_mul_f32 v[14:15], v[12:13], v[12:13]
	v_add_f32_e32 v10, v10, v11
	v_add_f32_e32 v10, v15, v10
	v_add_f32_e32 v10, v14, v10
	s_nop 1
	v_add_f32_dpp v10, v10, v10 quad_perm:[1,0,3,2] row_mask:0xf bank_mask:0xf
	s_nop 1
	v_add_f32_dpp v10, v10, v10 quad_perm:[2,3,0,1] row_mask:0xf bank_mask:0xf
	s_nop 1
	v_add_f32_dpp v10, v10, v10 row_half_mirror row_mask:0xf bank_mask:0xf
	s_nop 1
	v_add_f32_dpp v10, v10, v10 row_mirror row_mask:0xf bank_mask:0xf
	ds_bpermute_b32 v11, v53, v10
	s_waitcnt lgkmcnt(0)
	v_add_f32_e32 v10, v10, v11
	ds_bpermute_b32 v11, v54, v10
	s_waitcnt lgkmcnt(0)
	v_add_f32_e32 v10, v10, v11
	v_fmamk_f32 v10, v10, 0x3b800000, v176
	v_cmp_gt_f32_e32 vcc, s75, v10
	v_mul_f32_e32 v11, 0x4b800000, v10
	s_nop 0
	v_cndmask_b32_e32 v10, v10, v11, vcc
	v_rsq_f32_e32 v10, v10
	s_nop 0
	v_mul_f32_e32 v11, 0x45800000, v10
	v_cndmask_b32_e32 v10, v10, v11, vcc
	v_mul_f32_e32 v6, v6, v10
	v_mul_f32_e32 v6, v8, v6
	v_cvt_pk_bf16_f32 v6, v6, v2
	ds_write_b16 v9, v6 offset:16
	v_mul_f32_e32 v6, v7, v10
	v_mul_f32_e32 v6, v20, v6
	v_cvt_pk_bf16_f32 v6, v6, v2
	ds_write_b16 v9, v6 offset:16912
	v_mul_f32_e32 v6, v13, v10
	v_mul_f32_e32 v6, v21, v6
	v_cvt_pk_bf16_f32 v6, v6, v2
	ds_write_b16 v9, v6 offset:33808
	v_mul_f32_e32 v6, v12, v10
	v_mul_f32_e32 v6, v22, v6
	v_cvt_pk_bf16_f32 v6, v6, v2
	ds_write_b16 v9, v6 offset:50704
	v_lshl_add_u64 v[6:7], s[8:9], 0, v[40:41]
	v_lshl_add_u64 v[10:11], v[6:7], 0, s[96:97]
	s_waitcnt vmcnt(4)
	v_mov_b32_e32 v12, v207
	v_mov_b32_e32 v13, v206
	v_add_co_u32_e32 v6, vcc, s74, v6
	v_lshlrev_b32_e32 v12, 16, v12
	v_addc_co_u32_e32 v7, vcc, 0, v7, vcc
	v_mov_b32_e32 v6, v204
	s_nop 0
	v_mov_b32_e32 v7, v205
	v_lshlrev_b32_e32 v13, 16, v13
	v_mul_f32_e32 v14, 0x3d372713, v13
	v_mul_f32_e32 v14, v14, v13
	v_mov_b32_e32 v15, v13
	v_fmac_f32_e32 v15, v14, v15
	v_mul_f32_e32 v14, 0x3f4c422a, v15
	v_add_f32_e32 v14, v14, v14
	v_mul_f32_e32 v14, 0x3fb8aa3b, v14
	v_exp_f32_e32 v14, v14
	v_mov_b32_e32 v16, v12
	v_add_f32_e32 v14, 1.0, v14
	v_rcp_f32_e32 v15, v14
	v_mul_f32_e32 v14, 0x3d372713, v12
	v_mul_f32_e32 v14, v14, v12
	v_fmac_f32_e32 v16, v14, v16
	v_mul_f32_e32 v14, 0x3f4c422a, v16
	v_add_f32_e32 v14, v14, v14
	v_mul_f32_e32 v14, 0x3fb8aa3b, v14
	v_exp_f32_e32 v14, v14
	v_pk_mul_f32 v[12:13], v[12:13], 0.5 op_sel_hi:[1,0]
	v_add_f32_e32 v14, 1.0, v14
	v_rcp_f32_e32 v14, v14
	v_lshlrev_b32_e32 v6, 16, v6
	v_mul_f32_e32 v10, 0x3d372713, v6
	v_mul_f32_e32 v10, v10, v6
	v_mov_b32_e32 v11, v6
	v_lshlrev_b32_e32 v7, 16, v7
	v_fmac_f32_e32 v11, v10, v11
	v_mul_f32_e32 v10, 0x3f4c422a, v11
	v_mul_f32_e32 v11, 0x3d372713, v7
	v_mul_f32_e32 v11, v11, v7
	v_mov_b32_e32 v18, v7
	v_fmac_f32_e32 v18, v11, v18
	v_mul_f32_e32 v11, 0x3f4c422a, v18
	v_add_f32_e32 v10, v10, v10
	v_add_f32_e32 v11, v11, v11
	v_mul_f32_e32 v10, 0x3fb8aa3b, v10
	v_mul_f32_e32 v11, 0x3fb8aa3b, v11
	v_exp_f32_e32 v10, v10
	v_exp_f32_e32 v11, v11
	v_pk_mul_f32 v[6:7], v[6:7], 0.5 op_sel_hi:[1,0]
	v_pk_fma_f32 v[14:15], v[14:15], 2.0, 1.0 op_sel_hi:[1,0,0] neg_lo:[1,0,0] neg_hi:[1,0,0]
	v_add_f32_e32 v10, 1.0, v10
	v_add_f32_e32 v11, 1.0, v11
	v_rcp_f32_e32 v10, v10
	v_rcp_f32_e32 v11, v11
	v_pk_add_f32 v[14:15], v[14:15], 1.0 op_sel_hi:[1,0]
	v_pk_fma_f32 v[10:11], v[10:11], 2.0, 1.0 op_sel_hi:[1,0,0] neg_lo:[1,0,0] neg_hi:[1,0,0]
	s_nop 0
	v_pk_add_f32 v[10:11], v[10:11], 1.0 op_sel_hi:[1,0]
	v_pk_mul_f32 v[16:17], v[12:13], v[14:15]
	v_pk_mul_f32 v[18:19], v[6:7], v[10:11]
	s_nop 0
	v_add_f32_e32 v18, 0, v18
	v_add_f32_e32 v18, v18, v19
	v_add_f32_e32 v17, v18, v17
	v_add_f32_e32 v16, v17, v16
	s_nop 1
	v_add_f32_dpp v16, v16, v16 quad_perm:[1,0,3,2] row_mask:0xf bank_mask:0xf
	s_nop 1
	v_add_f32_dpp v16, v16, v16 quad_perm:[2,3,0,1] row_mask:0xf bank_mask:0xf
	s_nop 1
	v_add_f32_dpp v16, v16, v16 row_half_mirror row_mask:0xf bank_mask:0xf
	s_nop 1
	v_add_f32_dpp v16, v16, v16 row_mirror row_mask:0xf bank_mask:0xf
	ds_bpermute_b32 v17, v53, v16
	s_waitcnt lgkmcnt(0)
	v_add_f32_e32 v16, v16, v17
	ds_bpermute_b32 v17, v54, v16
	s_waitcnt lgkmcnt(0)
	v_add_f32_e32 v16, v16, v17
	v_mul_f32_e32 v16, 0x3b800000, v16
	v_pk_fma_f32 v[6:7], v[6:7], v[10:11], v[16:17] op_sel_hi:[1,1,0] neg_lo:[0,0,1] neg_hi:[0,0,1]
	v_pk_fma_f32 v[12:13], v[12:13], v[14:15], v[16:17] op_sel_hi:[1,1,0] neg_lo:[0,0,1] neg_hi:[0,0,1]
	v_pk_mul_f32 v[10:11], v[6:7], v[6:7]
	v_pk_mul_f32 v[14:15], v[12:13], v[12:13]
	v_add_f32_e32 v10, v10, v11
	v_add_f32_e32 v10, v15, v10
	v_add_f32_e32 v10, v14, v10
	s_nop 1
	v_add_f32_dpp v10, v10, v10 quad_perm:[1,0,3,2] row_mask:0xf bank_mask:0xf
	s_nop 1
	v_add_f32_dpp v10, v10, v10 quad_perm:[2,3,0,1] row_mask:0xf bank_mask:0xf
	s_nop 1
	v_add_f32_dpp v10, v10, v10 row_half_mirror row_mask:0xf bank_mask:0xf
	s_nop 1
	v_add_f32_dpp v10, v10, v10 row_mirror row_mask:0xf bank_mask:0xf
	ds_bpermute_b32 v11, v53, v10
	s_waitcnt lgkmcnt(0)
	v_add_f32_e32 v10, v10, v11
	ds_bpermute_b32 v11, v54, v10
	s_waitcnt lgkmcnt(0)
	v_add_f32_e32 v10, v10, v11
	v_fmamk_f32 v10, v10, 0x3b800000, v176
	v_cmp_gt_f32_e32 vcc, s75, v10
	v_mul_f32_e32 v11, 0x4b800000, v10
	s_nop 0
	v_cndmask_b32_e32 v10, v10, v11, vcc
	v_rsq_f32_e32 v10, v10
	s_nop 0
	v_mul_f32_e32 v11, 0x45800000, v10
	v_cndmask_b32_e32 v10, v10, v11, vcc
	v_mul_f32_e32 v6, v6, v10
	v_mul_f32_e32 v6, v8, v6
	v_cvt_pk_bf16_f32 v6, v6, v2
	ds_write_b16 v9, v6 offset:32
	v_mul_f32_e32 v6, v7, v10
	v_mul_f32_e32 v6, v20, v6
	v_cvt_pk_bf16_f32 v6, v6, v2
	ds_write_b16 v9, v6 offset:16928
	v_mul_f32_e32 v6, v13, v10
	v_mul_f32_e32 v6, v21, v6
	v_cvt_pk_bf16_f32 v6, v6, v2
	ds_write_b16 v9, v6 offset:33824
	v_mul_f32_e32 v6, v12, v10
	v_mul_f32_e32 v6, v22, v6
	v_cvt_pk_bf16_f32 v6, v6, v2
	ds_write_b16 v9, v6 offset:50720
	v_lshl_add_u64 v[6:7], s[2:3], 0, v[40:41]
	v_lshl_add_u64 v[10:11], v[6:7], 0, s[96:97]
	s_waitcnt vmcnt(0)
	v_mov_b32_e32 v12, v211
	v_mov_b32_e32 v13, v210
	v_add_co_u32_e32 v6, vcc, s74, v6
	s_mov_b64 s[2:3], 0x24000
	s_nop 0
	v_addc_co_u32_e32 v7, vcc, 0, v7, vcc
	v_mov_b32_e32 v6, v208
	s_nop 0
	v_mov_b32_e32 v7, v209
	v_lshl_add_u64 v[4:5], v[4:5], 0, s[2:3]
	v_lshlrev_b32_e32 v12, 16, v12
	v_lshlrev_b32_e32 v13, 16, v13
	v_mul_f32_e32 v14, 0x3d372713, v13
	v_mul_f32_e32 v14, v14, v13
	v_mov_b32_e32 v15, v13
	v_fmac_f32_e32 v15, v14, v15
	v_mul_f32_e32 v14, 0x3f4c422a, v15
	v_add_f32_e32 v14, v14, v14
	v_mul_f32_e32 v14, 0x3fb8aa3b, v14
	v_lshlrev_b32_e32 v6, 16, v6
	v_exp_f32_e32 v14, v14
	v_mul_f32_e32 v10, 0x3d372713, v6
	v_mul_f32_e32 v10, v10, v6
	v_mov_b32_e32 v11, v6
	v_lshlrev_b32_e32 v7, 16, v7
	v_fmac_f32_e32 v11, v10, v11
	v_mul_f32_e32 v10, 0x3f4c422a, v11
	v_mul_f32_e32 v11, 0x3d372713, v7
	v_add_f32_e32 v14, 1.0, v14
	v_mul_f32_e32 v11, v11, v7
	v_mov_b32_e32 v18, v7
	v_rcp_f32_e32 v15, v14
	v_mul_f32_e32 v14, 0x3d372713, v12
	v_fmac_f32_e32 v18, v11, v18
	v_mul_f32_e32 v14, v14, v12
	v_mov_b32_e32 v16, v12
	v_mul_f32_e32 v11, 0x3f4c422a, v18
	v_fmac_f32_e32 v16, v14, v16
	v_add_f32_e32 v10, v10, v10
	v_add_f32_e32 v11, v11, v11
	v_mul_f32_e32 v14, 0x3f4c422a, v16
	v_mul_f32_e32 v10, 0x3fb8aa3b, v10
	v_mul_f32_e32 v11, 0x3fb8aa3b, v11
	v_add_f32_e32 v14, v14, v14
	v_exp_f32_e32 v10, v10
	v_exp_f32_e32 v11, v11
	v_mul_f32_e32 v14, 0x3fb8aa3b, v14
	v_exp_f32_e32 v14, v14
	v_add_f32_e32 v10, 1.0, v10
	v_add_f32_e32 v11, 1.0, v11
	v_rcp_f32_e32 v10, v10
	v_rcp_f32_e32 v11, v11
	v_add_f32_e32 v14, 1.0, v14
	v_rcp_f32_e32 v14, v14
	v_pk_mul_f32 v[6:7], v[6:7], 0.5 op_sel_hi:[1,0]
	v_pk_fma_f32 v[10:11], v[10:11], 2.0, 1.0 op_sel_hi:[1,0,0] neg_lo:[1,0,0] neg_hi:[1,0,0]
	v_pk_mul_f32 v[12:13], v[12:13], 0.5 op_sel_hi:[1,0]
	v_pk_add_f32 v[10:11], v[10:11], 1.0 op_sel_hi:[1,0]
	v_pk_fma_f32 v[14:15], v[14:15], 2.0, 1.0 op_sel_hi:[1,0,0] neg_lo:[1,0,0] neg_hi:[1,0,0]
	v_pk_mul_f32 v[18:19], v[6:7], v[10:11]
	v_pk_add_f32 v[14:15], v[14:15], 1.0 op_sel_hi:[1,0]
	v_add_f32_e32 v18, 0, v18
	v_pk_mul_f32 v[16:17], v[12:13], v[14:15]
	v_add_f32_e32 v18, v18, v19
	v_add_f32_e32 v17, v18, v17
	v_add_f32_e32 v16, v17, v16
	s_nop 1
	v_add_f32_dpp v16, v16, v16 quad_perm:[1,0,3,2] row_mask:0xf bank_mask:0xf
	s_nop 1
	v_add_f32_dpp v16, v16, v16 quad_perm:[2,3,0,1] row_mask:0xf bank_mask:0xf
	s_nop 1
	v_add_f32_dpp v16, v16, v16 row_half_mirror row_mask:0xf bank_mask:0xf
	s_nop 1
	v_add_f32_dpp v16, v16, v16 row_mirror row_mask:0xf bank_mask:0xf
	ds_bpermute_b32 v17, v53, v16
	s_waitcnt lgkmcnt(0)
	v_add_f32_e32 v16, v16, v17
	ds_bpermute_b32 v17, v54, v16
	s_waitcnt lgkmcnt(0)
	v_add_f32_e32 v16, v16, v17
	v_mul_f32_e32 v16, 0x3b800000, v16
	v_pk_fma_f32 v[6:7], v[6:7], v[10:11], v[16:17] op_sel_hi:[1,1,0] neg_lo:[0,0,1] neg_hi:[0,0,1]
	v_pk_fma_f32 v[12:13], v[12:13], v[14:15], v[16:17] op_sel_hi:[1,1,0] neg_lo:[0,0,1] neg_hi:[0,0,1]
	v_pk_mul_f32 v[10:11], v[6:7], v[6:7]
	v_pk_mul_f32 v[14:15], v[12:13], v[12:13]
	v_add_f32_e32 v10, v10, v11
	v_add_f32_e32 v10, v15, v10
	v_add_f32_e32 v10, v14, v10
	s_nop 1
	v_add_f32_dpp v10, v10, v10 quad_perm:[1,0,3,2] row_mask:0xf bank_mask:0xf
	s_nop 1
	v_add_f32_dpp v10, v10, v10 quad_perm:[2,3,0,1] row_mask:0xf bank_mask:0xf
	s_nop 1
	v_add_f32_dpp v10, v10, v10 row_half_mirror row_mask:0xf bank_mask:0xf
	s_nop 1
	v_add_f32_dpp v10, v10, v10 row_mirror row_mask:0xf bank_mask:0xf
	ds_bpermute_b32 v11, v53, v10
	s_waitcnt lgkmcnt(0)
	v_add_f32_e32 v10, v10, v11
	ds_bpermute_b32 v11, v54, v10
	s_waitcnt lgkmcnt(0)
	v_add_f32_e32 v10, v10, v11
	v_fmamk_f32 v10, v10, 0x3b800000, v176
	v_cmp_gt_f32_e32 vcc, s75, v10
	v_mul_f32_e32 v11, 0x4b800000, v10
	s_nop 0
	v_cndmask_b32_e32 v10, v10, v11, vcc
	v_rsq_f32_e32 v10, v10
	s_nop 0
	v_mul_f32_e32 v11, 0x45800000, v10
	v_cndmask_b32_e32 v10, v10, v11, vcc
	v_mul_f32_e32 v6, v6, v10
	v_mul_f32_e32 v6, v8, v6
	v_cvt_pk_bf16_f32 v6, v6, v2
	ds_write_b16 v9, v6 offset:48
	v_mul_f32_e32 v6, v7, v10
	v_mul_f32_e32 v6, v20, v6
	v_cvt_pk_bf16_f32 v6, v6, v2
	ds_write_b16 v9, v6 offset:16944
	v_mul_f32_e32 v6, v13, v10
	v_mul_f32_e32 v6, v21, v6
	v_cvt_pk_bf16_f32 v6, v6, v2
	ds_write_b16 v9, v6 offset:33840
	v_mul_f32_e32 v6, v12, v10
	v_mul_f32_e32 v6, v22, v6
	v_cvt_pk_bf16_f32 v6, v6, v2
	ds_write_b16 v9, v6 offset:50736
	v_add_u32_e32 v9, 64, v9
	s_cbranch_scc0 .LBB0_287
	v_mov_b32_e32 v37, v2
	v_lshlrev_b64 v[4:5], 11, v[36:37]
	v_mad_u64_u32 v[44:45], s[2:3], v36, s61, v[38:39]
	v_lshl_add_u64 v[42:43], v[34:35], 0, v[4:5]
	s_mov_b64 s[2:3], 0
	v_mov_b32_e32 v37, v56
	v_mov_b64_e32 v[46:47], v[32:33]
	v_mov_b64_e32 v[48:49], v[30:31]
	s_waitcnt lgkmcnt(0)
	s_barrier
	s_branch .LBB0_290
